# grid barrier: every workgroup writes back its XCD L2 on arrival (distributed flush) on top of v67
# baseline (speedup 1.0000x reference)
; __device__ __forceinline__ unsigned xb_add(unsigned* p, unsigned v) { return __hip_atomic_fetch_add(p, v, __ATOMIC_RELAXED, __HIP_MEMORY_SCOPE_AGENT); }
; __device__ __forceinline__ void xcd_barrier(unsigned* bar, unsigned x, volatile LAS unsigned* st) {
;     ...
;     if (threadIdx.x == 0) {
;         __builtin_amdgcn_s_waitcnt(0);
;         unsigned nloc = st[0], nx = st[1];
;         if (nloc == 0u) { xcd_barrier_complete(bar, x, nloc, nx); st[0] = nloc; st[1] = nx; }
;         const unsigned old = xb_add(&bar[XB_XSUB(x)], 1u);
.LBB0_862:
	s_mov_b64 s[6:7], exec
	s_lshl_b32 s2, s2, 8
	v_readlane_b32 s3, v253, 32
	v_mbcnt_lo_u32_b32 v1, s6, 0
	s_add_u32 s4, s3, s2
	v_readlane_b32 s2, v253, 33
	v_mbcnt_hi_u32_b32 v1, s7, v1
	s_addc_u32 s5, s2, 0
	v_cmp_eq_u32_e32 vcc, 0, v1
	s_and_saveexec_b64 s[8:9], vcc
	s_cbranch_execz .LBB0_864
	s_bcnt1_i32_b64 s2, s[6:7]
	v_mov_b32_e32 v3, s2
	v_mov_b32_e32 v4, 0x1000
	buffer_wbl2 sc1
	s_waitcnt vmcnt(0)
	global_atomic_add v3, v4, v3, s[4:5] offset:1024 sc0
